# v28 + out-proj epilogue: both residual pieces of a row loaded together (second at offset:256), counted wait
# speedup vs baseline: 1.0286x; 1.0158x over previous
.LBB0_601:
	s_or_b64 exec, exec, s[22:23]
	s_lshl_b32 s4, s42, 5
	v_readlane_b32 s36, v254, 10
	s_lshl_b32 s5, s12, 8
	s_lshl_b32 s64, s93, 11
	v_readlane_b32 s40, v254, 14
	v_readlane_b32 s41, v254, 15
	v_readlane_b32 s44, v254, 18
	v_readlane_b32 s45, v254, 19
	v_readlane_b32 s46, v254, 20
	v_readlane_b32 s47, v254, 21
	v_readlane_b32 s48, v254, 22
	v_readlane_b32 s49, v254, 23
	v_lshrrev_b32_e32 v128, 1, v142
	s_or_b32 s4, s5, s4
	s_lshl_b64 s[56:57], s[64:65], 2
	v_readlane_b32 s37, v254, 11
	v_readlane_b32 s38, v254, 12
	v_readlane_b32 s39, v254, 13
	s_mov_b64 s[48:49], s[40:41]
	v_and_or_b32 v174, v128, 24, s4
	s_add_u32 s4, s48, s56
	s_addc_u32 s5, s49, s57
	v_ashrrev_i32_e32 v175, 31, v174
	s_waitcnt lgkmcnt(0)
	s_barrier
	v_lshl_add_u64 v[132:133], v[174:175], 2, s[4:5]
	global_load_dwordx4 v[136:139], v[132:133], off offset:16
	global_load_dwordx4 v[140:143], v[132:133], off
	global_load_dwordx4 v[128:131], v[132:133], off offset:528
	s_nop 0
	global_load_dwordx4 v[132:135], v[132:133], off offset:512
	v_lshl_add_u32 v237, v188, 2, 0
	ds_read_b32 v160, v237 offset:4096
	v_add_u32_e32 v220, s26, v188
	v_ashrrev_i32_e32 v221, 31, v220
	v_lshlrev_b64 v[144:145], 11, v[220:221]
	v_readlane_b32 s4, v255, 14
	s_cmp_lg_u32 s93, 0
	v_lshl_add_u64 v[164:165], v[144:145], 0, v[174:175]
	v_readlane_b32 s5, v255, 15
	s_cselect_b64 s[24:25], -1, 0
	s_cmp_eq_u32 s93, 0
	v_lshl_add_u64 v[168:169], v[164:165], 1, s[4:5]
	v_readlane_b32 s42, v254, 16
	v_readlane_b32 s43, v254, 17
	v_readlane_b32 s50, v254, 24
	v_readlane_b32 s51, v254, 25
	s_mov_b64 s[46:47], s[38:39]
	s_mov_b64 s[44:45], s[36:37]
	s_cbranch_scc1 .LBB0_680
	global_load_dwordx4 v[144:147], v[168:169], off
	global_load_dwordx4 v[152:155], v[168:169], off offset:256
	s_waitcnt vmcnt(1)
	v_lshlrev_b32_e32 v148, 16, v144
	v_and_b32_e32 v149, 0xffff0000, v144
	v_lshlrev_b32_e32 v150, 16, v145
	v_and_b32_e32 v151, 0xffff0000, v145
	v_lshlrev_b32_e32 v144, 16, v146
	v_and_b32_e32 v145, 0xffff0000, v146
	v_lshlrev_b32_e32 v146, 16, v147
	v_and_b32_e32 v147, 0xffff0000, v147
	s_cbranch_execnz .LBB0_604

.LBB0_604:
	v_readlane_b32 s4, v255, 14
	v_or_b32_e32 v166, 0x80, v164
	v_mov_b32_e32 v167, v165
	v_readlane_b32 s5, v255, 15
	s_and_b64 vcc, exec, s[24:25]
	s_nop 0
	v_lshl_add_u64 v[172:173], v[166:167], 1, s[4:5]
	s_cbranch_vccz .LBB0_681
	s_waitcnt vmcnt(0)
	v_lshlrev_b32_e32 v156, 16, v152
	v_and_b32_e32 v157, 0xffff0000, v152
	v_lshlrev_b32_e32 v158, 16, v153
	v_and_b32_e32 v159, 0xffff0000, v153
	v_lshlrev_b32_e32 v152, 16, v154
	v_and_b32_e32 v153, 0xffff0000, v154
	v_lshlrev_b32_e32 v154, 16, v155
	v_and_b32_e32 v155, 0xffff0000, v155
	s_cbranch_execnz .LBB0_607

.LBB0_607:
	s_waitcnt lgkmcnt(0)
	v_pk_mul_f32 v[120:121], v[120:121], v[160:161] op_sel_hi:[1,0]
	v_pk_mul_f32 v[122:123], v[122:123], v[160:161] op_sel_hi:[1,0]
	v_pk_mul_f32 v[124:125], v[124:125], v[160:161] op_sel_hi:[1,0]
	v_pk_mul_f32 v[126:127], v[126:127], v[160:161] op_sel_hi:[1,0]
	v_pk_mul_f32 v[108:109], v[108:109], v[160:161] op_sel_hi:[1,0]
	v_pk_mul_f32 v[110:111], v[110:111], v[160:161] op_sel_hi:[1,0]
	v_pk_mul_f32 v[116:117], v[116:117], v[160:161] op_sel_hi:[1,0]
	v_pk_mul_f32 v[118:119], v[118:119], v[160:161] op_sel_hi:[1,0]
	s_waitcnt vmcnt(0)
	v_pk_fma_f32 v[122:123], v[142:143], v[122:123], v[150:151]
	v_pk_fma_f32 v[120:121], v[140:141], v[120:121], v[148:149]
	v_pk_fma_f32 v[126:127], v[138:139], v[126:127], v[146:147]
	v_pk_fma_f32 v[124:125], v[136:137], v[124:125], v[144:145]
	v_pk_fma_f32 v[110:111], v[134:135], v[110:111], v[158:159]
	v_pk_fma_f32 v[108:109], v[132:133], v[108:109], v[156:157]
	v_pk_fma_f32 v[118:119], v[130:131], v[118:119], v[154:155]
	v_pk_fma_f32 v[116:117], v[128:129], v[116:117], v[152:153]
	v_add3_u32 v144, s26, v188, 16
	ds_read_b32 v160, v237 offset:4160
	v_ashrrev_i32_e32 v145, 31, v144
	v_lshlrev_b64 v[144:145], 11, v[144:145]
	v_readlane_b32 s4, v255, 14
	v_lshl_add_u64 v[170:171], v[144:145], 0, v[174:175]
	v_readlane_b32 s5, v255, 15
	s_and_b64 vcc, exec, s[24:25]
	s_nop 0
	v_lshl_add_u64 v[178:179], v[170:171], 1, s[4:5]
	s_cbranch_vccz .LBB0_682
	global_load_dwordx4 v[144:147], v[178:179], off
	global_load_dwordx4 v[152:155], v[178:179], off offset:256
	s_waitcnt vmcnt(1)
	v_lshlrev_b32_e32 v148, 16, v144
	v_and_b32_e32 v149, 0xffff0000, v144
	v_lshlrev_b32_e32 v150, 16, v145
	v_and_b32_e32 v151, 0xffff0000, v145
	v_lshlrev_b32_e32 v144, 16, v146
	v_and_b32_e32 v145, 0xffff0000, v146
	v_lshlrev_b32_e32 v146, 16, v147
	v_and_b32_e32 v147, 0xffff0000, v147
	s_cbranch_execnz .LBB0_610

.LBB0_610:
	v_readlane_b32 s4, v255, 14
	v_or_b32_e32 v176, 0x80, v170
	v_mov_b32_e32 v177, v171
	v_readlane_b32 s5, v255, 15
	s_and_b64 vcc, exec, s[24:25]
	s_nop 0
	v_lshl_add_u64 v[180:181], v[176:177], 1, s[4:5]
	s_cbranch_vccz .LBB0_683
	s_waitcnt vmcnt(0)
	v_lshlrev_b32_e32 v156, 16, v152
	v_and_b32_e32 v157, 0xffff0000, v152
	v_lshlrev_b32_e32 v158, 16, v153
	v_and_b32_e32 v159, 0xffff0000, v153
	v_lshlrev_b32_e32 v152, 16, v154
	v_and_b32_e32 v153, 0xffff0000, v154
	v_lshlrev_b32_e32 v154, 16, v155
	v_and_b32_e32 v155, 0xffff0000, v155
	s_cbranch_execnz .LBB0_613

.LBB0_613:
	s_waitcnt lgkmcnt(0)
	v_pk_mul_f32 v[112:113], v[112:113], v[160:161] op_sel_hi:[1,0]
	v_pk_mul_f32 v[114:115], v[114:115], v[160:161] op_sel_hi:[1,0]
	v_pk_mul_f32 v[104:105], v[104:105], v[160:161] op_sel_hi:[1,0]
	v_pk_mul_f32 v[106:107], v[106:107], v[160:161] op_sel_hi:[1,0]
	v_pk_mul_f32 v[100:101], v[100:101], v[160:161] op_sel_hi:[1,0]
	v_pk_mul_f32 v[102:103], v[102:103], v[160:161] op_sel_hi:[1,0]
	v_pk_mul_f32 v[96:97], v[96:97], v[160:161] op_sel_hi:[1,0]
	v_pk_mul_f32 v[98:99], v[98:99], v[160:161] op_sel_hi:[1,0]
	s_waitcnt vmcnt(0)
	v_pk_fma_f32 v[114:115], v[142:143], v[114:115], v[150:151]
	v_pk_fma_f32 v[112:113], v[140:141], v[112:113], v[148:149]
	v_pk_fma_f32 v[106:107], v[138:139], v[106:107], v[146:147]
	v_pk_fma_f32 v[104:105], v[136:137], v[104:105], v[144:145]
	v_pk_fma_f32 v[102:103], v[134:135], v[102:103], v[158:159]
	v_pk_fma_f32 v[100:101], v[132:133], v[100:101], v[156:157]
	v_pk_fma_f32 v[98:99], v[130:131], v[98:99], v[154:155]
	v_pk_fma_f32 v[96:97], v[128:129], v[96:97], v[152:153]
	v_add3_u32 v144, s26, v188, 32
	ds_read_b32 v160, v237 offset:4224
	v_ashrrev_i32_e32 v145, 31, v144
	v_lshlrev_b64 v[144:145], 11, v[144:145]
	v_readlane_b32 s4, v255, 14
	v_lshl_add_u64 v[182:183], v[144:145], 0, v[174:175]
	v_readlane_b32 s5, v255, 15
	s_and_b64 vcc, exec, s[24:25]
	s_nop 0
	v_lshl_add_u64 v[186:187], v[182:183], 1, s[4:5]
	s_cbranch_vccz .LBB0_684
	global_load_dwordx4 v[144:147], v[186:187], off
	global_load_dwordx4 v[152:155], v[186:187], off offset:256
	s_waitcnt vmcnt(1)
	v_lshlrev_b32_e32 v148, 16, v144
	v_and_b32_e32 v149, 0xffff0000, v144
	v_lshlrev_b32_e32 v150, 16, v145
	v_and_b32_e32 v151, 0xffff0000, v145
	v_lshlrev_b32_e32 v144, 16, v146
	v_and_b32_e32 v145, 0xffff0000, v146
	v_lshlrev_b32_e32 v146, 16, v147
	v_and_b32_e32 v147, 0xffff0000, v147
	s_cbranch_execnz .LBB0_616

.LBB0_616:
	v_readlane_b32 s4, v255, 14
	v_or_b32_e32 v184, 0x80, v182
	v_mov_b32_e32 v185, v183
	v_readlane_b32 s5, v255, 15
	s_and_b64 vcc, exec, s[24:25]
	s_nop 0
	v_lshl_add_u64 v[190:191], v[184:185], 1, s[4:5]
	s_cbranch_vccz .LBB0_685
	s_waitcnt vmcnt(0)
	v_lshlrev_b32_e32 v156, 16, v152
	v_and_b32_e32 v157, 0xffff0000, v152
	v_lshlrev_b32_e32 v158, 16, v153
	v_and_b32_e32 v159, 0xffff0000, v153
	v_lshlrev_b32_e32 v152, 16, v154
	v_and_b32_e32 v153, 0xffff0000, v154
	v_lshlrev_b32_e32 v154, 16, v155
	v_and_b32_e32 v155, 0xffff0000, v155
	s_cbranch_execnz .LBB0_619

.LBB0_619:
	s_waitcnt lgkmcnt(0)
	v_pk_mul_f32 v[92:93], v[92:93], v[160:161] op_sel_hi:[1,0]
	v_pk_mul_f32 v[94:95], v[94:95], v[160:161] op_sel_hi:[1,0]
	v_pk_mul_f32 v[88:89], v[88:89], v[160:161] op_sel_hi:[1,0]
	v_pk_mul_f32 v[90:91], v[90:91], v[160:161] op_sel_hi:[1,0]
	v_pk_mul_f32 v[84:85], v[84:85], v[160:161] op_sel_hi:[1,0]
	v_pk_mul_f32 v[86:87], v[86:87], v[160:161] op_sel_hi:[1,0]
	v_pk_mul_f32 v[80:81], v[80:81], v[160:161] op_sel_hi:[1,0]
	v_pk_mul_f32 v[82:83], v[82:83], v[160:161] op_sel_hi:[1,0]
	s_waitcnt vmcnt(0)
	v_pk_fma_f32 v[94:95], v[142:143], v[94:95], v[150:151]
	v_pk_fma_f32 v[92:93], v[140:141], v[92:93], v[148:149]
	v_pk_fma_f32 v[90:91], v[138:139], v[90:91], v[146:147]
	v_pk_fma_f32 v[88:89], v[136:137], v[88:89], v[144:145]
	v_pk_fma_f32 v[86:87], v[134:135], v[86:87], v[158:159]
	v_pk_fma_f32 v[84:85], v[132:133], v[84:85], v[156:157]
	v_pk_fma_f32 v[82:83], v[130:131], v[82:83], v[154:155]
	v_pk_fma_f32 v[80:81], v[128:129], v[80:81], v[152:153]
	v_add3_u32 v144, s26, v188, 48
	ds_read_b32 v160, v237 offset:4288
	v_ashrrev_i32_e32 v145, 31, v144
	v_lshlrev_b64 v[144:145], 11, v[144:145]
	v_readlane_b32 s4, v255, 14
	v_lshl_add_u64 v[188:189], v[144:145], 0, v[174:175]
	v_readlane_b32 s5, v255, 15
	s_and_b64 vcc, exec, s[24:25]
	s_nop 0
	v_lshl_add_u64 v[194:195], v[188:189], 1, s[4:5]
	s_cbranch_vccz .LBB0_686
	global_load_dwordx4 v[144:147], v[194:195], off
	global_load_dwordx4 v[152:155], v[194:195], off offset:256
	s_waitcnt vmcnt(1)
	v_lshlrev_b32_e32 v148, 16, v144
	v_and_b32_e32 v149, 0xffff0000, v144
	v_lshlrev_b32_e32 v150, 16, v145
	v_and_b32_e32 v151, 0xffff0000, v145
	v_lshlrev_b32_e32 v144, 16, v146
	v_and_b32_e32 v145, 0xffff0000, v146
	v_lshlrev_b32_e32 v146, 16, v147
	v_and_b32_e32 v147, 0xffff0000, v147
	s_cbranch_execnz .LBB0_622

.LBB0_622:
	v_readlane_b32 s4, v255, 14
	v_or_b32_e32 v192, 0x80, v188
	v_mov_b32_e32 v193, v189
	v_readlane_b32 s5, v255, 15
	s_and_b64 vcc, exec, s[24:25]
	s_nop 0
	v_lshl_add_u64 v[198:199], v[192:193], 1, s[4:5]
	s_cbranch_vccz .LBB0_687
	s_waitcnt vmcnt(0)
	v_lshlrev_b32_e32 v156, 16, v152
	v_and_b32_e32 v157, 0xffff0000, v152
	v_lshlrev_b32_e32 v158, 16, v153
	v_and_b32_e32 v159, 0xffff0000, v153
	v_lshlrev_b32_e32 v152, 16, v154
	v_and_b32_e32 v153, 0xffff0000, v154
	v_lshlrev_b32_e32 v154, 16, v155
	v_and_b32_e32 v155, 0xffff0000, v155
	s_cbranch_execnz .LBB0_625

.LBB0_625:
	s_waitcnt lgkmcnt(0)
	v_pk_mul_f32 v[76:77], v[76:77], v[160:161] op_sel_hi:[1,0]
	v_pk_mul_f32 v[78:79], v[78:79], v[160:161] op_sel_hi:[1,0]
	v_pk_mul_f32 v[72:73], v[72:73], v[160:161] op_sel_hi:[1,0]
	v_pk_mul_f32 v[74:75], v[74:75], v[160:161] op_sel_hi:[1,0]
	v_pk_mul_f32 v[68:69], v[68:69], v[160:161] op_sel_hi:[1,0]
	v_pk_mul_f32 v[70:71], v[70:71], v[160:161] op_sel_hi:[1,0]
	v_pk_mul_f32 v[64:65], v[64:65], v[160:161] op_sel_hi:[1,0]
	v_pk_mul_f32 v[66:67], v[66:67], v[160:161] op_sel_hi:[1,0]
	s_waitcnt vmcnt(0)
	v_pk_fma_f32 v[78:79], v[142:143], v[78:79], v[150:151]
	v_pk_fma_f32 v[76:77], v[140:141], v[76:77], v[148:149]
	v_pk_fma_f32 v[74:75], v[138:139], v[74:75], v[146:147]
	v_pk_fma_f32 v[72:73], v[136:137], v[72:73], v[144:145]
	v_pk_fma_f32 v[70:71], v[134:135], v[70:71], v[158:159]
	v_pk_fma_f32 v[68:69], v[132:133], v[68:69], v[156:157]
	v_pk_fma_f32 v[66:67], v[130:131], v[66:67], v[154:155]
	v_pk_fma_f32 v[64:65], v[128:129], v[64:65], v[152:153]
	v_add_u32_e32 v144, 0x80, v220
	ds_read_b32 v160, v237 offset:4608
	v_ashrrev_i32_e32 v145, 31, v144
	v_lshlrev_b64 v[144:145], 11, v[144:145]
	v_readlane_b32 s4, v255, 14
	v_lshl_add_u64 v[196:197], v[144:145], 0, v[174:175]
	v_readlane_b32 s5, v255, 15
	s_and_b64 vcc, exec, s[24:25]
	s_nop 0
	v_lshl_add_u64 v[202:203], v[196:197], 1, s[4:5]
	s_cbranch_vccz .LBB0_688
	global_load_dwordx4 v[144:147], v[202:203], off
	global_load_dwordx4 v[152:155], v[202:203], off offset:256
	s_waitcnt vmcnt(1)
	v_lshlrev_b32_e32 v148, 16, v144
	v_and_b32_e32 v149, 0xffff0000, v144
	v_lshlrev_b32_e32 v150, 16, v145
	v_and_b32_e32 v151, 0xffff0000, v145
	v_lshlrev_b32_e32 v144, 16, v146
	v_and_b32_e32 v145, 0xffff0000, v146
	v_lshlrev_b32_e32 v146, 16, v147
	v_and_b32_e32 v147, 0xffff0000, v147
	s_cbranch_execnz .LBB0_628

.LBB0_628:
	v_readlane_b32 s4, v255, 14
	v_or_b32_e32 v200, 0x80, v196
	v_mov_b32_e32 v201, v197
	v_readlane_b32 s5, v255, 15
	s_and_b64 vcc, exec, s[24:25]
	s_nop 0
	v_lshl_add_u64 v[206:207], v[200:201], 1, s[4:5]
	s_cbranch_vccz .LBB0_689
	s_waitcnt vmcnt(0)
	v_lshlrev_b32_e32 v156, 16, v152
	v_and_b32_e32 v157, 0xffff0000, v152
	v_lshlrev_b32_e32 v158, 16, v153
	v_and_b32_e32 v159, 0xffff0000, v153
	v_lshlrev_b32_e32 v152, 16, v154
	v_and_b32_e32 v153, 0xffff0000, v154
	v_lshlrev_b32_e32 v154, 16, v155
	v_and_b32_e32 v155, 0xffff0000, v155
	s_cbranch_execnz .LBB0_631

.LBB0_631:
	s_waitcnt lgkmcnt(0)
	v_pk_mul_f32 v[60:61], v[60:61], v[160:161] op_sel_hi:[1,0]
	v_pk_mul_f32 v[62:63], v[62:63], v[160:161] op_sel_hi:[1,0]
	v_pk_mul_f32 v[56:57], v[56:57], v[160:161] op_sel_hi:[1,0]
	v_pk_mul_f32 v[58:59], v[58:59], v[160:161] op_sel_hi:[1,0]
	v_pk_mul_f32 v[52:53], v[52:53], v[160:161] op_sel_hi:[1,0]
	v_pk_mul_f32 v[54:55], v[54:55], v[160:161] op_sel_hi:[1,0]
	v_pk_mul_f32 v[48:49], v[48:49], v[160:161] op_sel_hi:[1,0]
	v_pk_mul_f32 v[50:51], v[50:51], v[160:161] op_sel_hi:[1,0]
	s_waitcnt vmcnt(0)
	v_pk_fma_f32 v[62:63], v[142:143], v[62:63], v[150:151]
	v_pk_fma_f32 v[60:61], v[140:141], v[60:61], v[148:149]
	v_pk_fma_f32 v[58:59], v[138:139], v[58:59], v[146:147]
	v_pk_fma_f32 v[56:57], v[136:137], v[56:57], v[144:145]
	v_pk_fma_f32 v[54:55], v[134:135], v[54:55], v[158:159]
	v_pk_fma_f32 v[52:53], v[132:133], v[52:53], v[156:157]
	v_pk_fma_f32 v[50:51], v[130:131], v[50:51], v[154:155]
	v_pk_fma_f32 v[48:49], v[128:129], v[48:49], v[152:153]
	v_add_u32_e32 v144, 0x90, v220
	ds_read_b32 v160, v237 offset:4672
	v_ashrrev_i32_e32 v145, 31, v144
	v_lshlrev_b64 v[144:145], 11, v[144:145]
	v_readlane_b32 s4, v255, 14
	v_lshl_add_u64 v[204:205], v[144:145], 0, v[174:175]
	v_readlane_b32 s5, v255, 15
	s_and_b64 vcc, exec, s[24:25]
	s_nop 0
	v_lshl_add_u64 v[210:211], v[204:205], 1, s[4:5]
	s_cbranch_vccz .LBB0_690
	global_load_dwordx4 v[144:147], v[210:211], off
	global_load_dwordx4 v[152:155], v[210:211], off offset:256
	s_waitcnt vmcnt(1)
	v_lshlrev_b32_e32 v148, 16, v144
	v_and_b32_e32 v149, 0xffff0000, v144
	v_lshlrev_b32_e32 v150, 16, v145
	v_and_b32_e32 v151, 0xffff0000, v145
	v_lshlrev_b32_e32 v144, 16, v146
	v_and_b32_e32 v145, 0xffff0000, v146
	v_lshlrev_b32_e32 v146, 16, v147
	v_and_b32_e32 v147, 0xffff0000, v147
	s_cbranch_execnz .LBB0_634

.LBB0_634:
	v_readlane_b32 s4, v255, 14
	v_or_b32_e32 v208, 0x80, v204
	v_mov_b32_e32 v209, v205
	v_readlane_b32 s5, v255, 15
	s_and_b64 vcc, exec, s[24:25]
	s_nop 0
	v_lshl_add_u64 v[214:215], v[208:209], 1, s[4:5]
	s_cbranch_vccz .LBB0_691
	s_waitcnt vmcnt(0)
	v_lshlrev_b32_e32 v156, 16, v152
	v_and_b32_e32 v157, 0xffff0000, v152
	v_lshlrev_b32_e32 v158, 16, v153
	v_and_b32_e32 v159, 0xffff0000, v153
	v_lshlrev_b32_e32 v152, 16, v154
	v_and_b32_e32 v153, 0xffff0000, v154
	v_lshlrev_b32_e32 v154, 16, v155
	v_and_b32_e32 v155, 0xffff0000, v155
	s_cbranch_execnz .LBB0_637

.LBB0_637:
	s_waitcnt lgkmcnt(0)
	v_pk_mul_f32 v[44:45], v[44:45], v[160:161] op_sel_hi:[1,0]
	v_pk_mul_f32 v[46:47], v[46:47], v[160:161] op_sel_hi:[1,0]
	v_pk_mul_f32 v[40:41], v[40:41], v[160:161] op_sel_hi:[1,0]
	v_pk_mul_f32 v[42:43], v[42:43], v[160:161] op_sel_hi:[1,0]
	v_pk_mul_f32 v[36:37], v[36:37], v[160:161] op_sel_hi:[1,0]
	v_pk_mul_f32 v[38:39], v[38:39], v[160:161] op_sel_hi:[1,0]
	v_pk_mul_f32 v[32:33], v[32:33], v[160:161] op_sel_hi:[1,0]
	v_pk_mul_f32 v[34:35], v[34:35], v[160:161] op_sel_hi:[1,0]
	s_waitcnt vmcnt(0)
	v_pk_fma_f32 v[46:47], v[142:143], v[46:47], v[150:151]
	v_pk_fma_f32 v[44:45], v[140:141], v[44:45], v[148:149]
	v_pk_fma_f32 v[42:43], v[138:139], v[42:43], v[146:147]
	v_pk_fma_f32 v[40:41], v[136:137], v[40:41], v[144:145]
	v_pk_fma_f32 v[38:39], v[134:135], v[38:39], v[158:159]
	v_pk_fma_f32 v[36:37], v[132:133], v[36:37], v[156:157]
	v_pk_fma_f32 v[34:35], v[130:131], v[34:35], v[154:155]
	v_pk_fma_f32 v[32:33], v[128:129], v[32:33], v[152:153]
	v_add_u32_e32 v144, 0xa0, v220
	ds_read_b32 v160, v237 offset:4736
	v_ashrrev_i32_e32 v145, 31, v144
	v_lshlrev_b64 v[144:145], 11, v[144:145]
	v_readlane_b32 s4, v255, 14
	v_lshl_add_u64 v[212:213], v[144:145], 0, v[174:175]
	v_readlane_b32 s5, v255, 15
	s_and_b64 vcc, exec, s[24:25]
	s_nop 0
	v_lshl_add_u64 v[218:219], v[212:213], 1, s[4:5]
	s_cbranch_vccz .LBB0_692
	global_load_dwordx4 v[144:147], v[218:219], off
	global_load_dwordx4 v[152:155], v[218:219], off offset:256
	s_waitcnt vmcnt(1)
	v_lshlrev_b32_e32 v148, 16, v144
	v_and_b32_e32 v149, 0xffff0000, v144
	v_lshlrev_b32_e32 v150, 16, v145
	v_and_b32_e32 v151, 0xffff0000, v145
	v_lshlrev_b32_e32 v144, 16, v146
	v_and_b32_e32 v145, 0xffff0000, v146
	v_lshlrev_b32_e32 v146, 16, v147
	v_and_b32_e32 v147, 0xffff0000, v147
	s_cbranch_execnz .LBB0_640

.LBB0_640:
	v_readlane_b32 s4, v255, 14
	v_or_b32_e32 v216, 0x80, v212
	v_mov_b32_e32 v217, v213
	v_readlane_b32 s5, v255, 15
	s_and_b64 vcc, exec, s[24:25]
	s_nop 0
	v_lshl_add_u64 v[222:223], v[216:217], 1, s[4:5]
	s_cbranch_vccz .LBB0_693
	s_waitcnt vmcnt(0)
	v_lshlrev_b32_e32 v156, 16, v152
	v_and_b32_e32 v157, 0xffff0000, v152
	v_lshlrev_b32_e32 v158, 16, v153
	v_and_b32_e32 v159, 0xffff0000, v153
	v_lshlrev_b32_e32 v152, 16, v154
	v_and_b32_e32 v153, 0xffff0000, v154
	v_lshlrev_b32_e32 v154, 16, v155
	v_and_b32_e32 v155, 0xffff0000, v155
	s_cbranch_execnz .LBB0_643

.LBB0_643:
	s_waitcnt lgkmcnt(0)
	v_pk_mul_f32 v[28:29], v[28:29], v[160:161] op_sel_hi:[1,0]
	v_pk_mul_f32 v[30:31], v[30:31], v[160:161] op_sel_hi:[1,0]
	v_pk_mul_f32 v[24:25], v[24:25], v[160:161] op_sel_hi:[1,0]
	v_pk_mul_f32 v[26:27], v[26:27], v[160:161] op_sel_hi:[1,0]
	v_pk_mul_f32 v[20:21], v[20:21], v[160:161] op_sel_hi:[1,0]
	v_pk_mul_f32 v[22:23], v[22:23], v[160:161] op_sel_hi:[1,0]
	v_pk_mul_f32 v[16:17], v[16:17], v[160:161] op_sel_hi:[1,0]
	v_pk_mul_f32 v[18:19], v[18:19], v[160:161] op_sel_hi:[1,0]
	s_waitcnt vmcnt(0)
	v_pk_fma_f32 v[30:31], v[142:143], v[30:31], v[150:151]
	v_pk_fma_f32 v[28:29], v[140:141], v[28:29], v[148:149]
	v_pk_fma_f32 v[26:27], v[138:139], v[26:27], v[146:147]
	v_pk_fma_f32 v[24:25], v[136:137], v[24:25], v[144:145]
	v_pk_fma_f32 v[22:23], v[134:135], v[22:23], v[158:159]
	v_pk_fma_f32 v[20:21], v[132:133], v[20:21], v[156:157]
	v_pk_fma_f32 v[18:19], v[130:131], v[18:19], v[154:155]
	v_pk_fma_f32 v[16:17], v[128:129], v[16:17], v[152:153]
	v_add_u32_e32 v144, 0xb0, v220
	ds_read_b32 v160, v237 offset:4800
	v_ashrrev_i32_e32 v145, 31, v144
	v_lshlrev_b64 v[144:145], 11, v[144:145]
	v_readlane_b32 s4, v255, 14
	v_lshl_add_u64 v[220:221], v[144:145], 0, v[174:175]
	v_readlane_b32 s5, v255, 15
	s_and_b64 vcc, exec, s[24:25]
	s_nop 0
	v_lshl_add_u64 v[226:227], v[220:221], 1, s[4:5]
	s_cbranch_vccz .LBB0_694
	global_load_dwordx4 v[144:147], v[226:227], off
	global_load_dwordx4 v[152:155], v[226:227], off offset:256
	s_waitcnt vmcnt(1)
	v_lshlrev_b32_e32 v148, 16, v144
	v_and_b32_e32 v149, 0xffff0000, v144
	v_lshlrev_b32_e32 v150, 16, v145
	v_and_b32_e32 v151, 0xffff0000, v145
	v_lshlrev_b32_e32 v144, 16, v146
	v_and_b32_e32 v145, 0xffff0000, v146
	v_lshlrev_b32_e32 v146, 16, v147
	v_and_b32_e32 v147, 0xffff0000, v147
	s_cbranch_execnz .LBB0_646

.LBB0_646:
	v_readlane_b32 s4, v255, 14
	v_or_b32_e32 v224, 0x80, v220
	v_mov_b32_e32 v225, v221
	v_readlane_b32 s5, v255, 15
	s_and_b64 vcc, exec, s[24:25]
	s_nop 0
	v_lshl_add_u64 v[228:229], v[224:225], 1, s[4:5]
	s_cbranch_vccz .LBB0_695
	s_waitcnt vmcnt(0)
	v_lshlrev_b32_e32 v156, 16, v152
	v_and_b32_e32 v157, 0xffff0000, v152
	v_lshlrev_b32_e32 v158, 16, v153
	v_and_b32_e32 v159, 0xffff0000, v153
	v_lshlrev_b32_e32 v152, 16, v154
	v_and_b32_e32 v153, 0xffff0000, v154
	v_lshlrev_b32_e32 v154, 16, v155
	v_and_b32_e32 v155, 0xffff0000, v155
	s_cbranch_execnz .LBB0_649
